# same as previous best plus guards: BR-B tail move and gate sample split only when the grid has 256 workgroups (falls back to the original unit order otherwise)
# baseline (speedup 1.0000x reference)
.LBB0_735:
	s_add_i32 s69, s69, s34
	s_add_i32 s3, s3, s31
	s_add_i32 s40, s40, s31
	s_add_i32 s41, s41, s31
	s_add_i32 s62, s62, s31
	s_add_i32 s63, s63, s31
	s_add_i32 s64, s64, s31
	s_add_i32 s65, s65, s31
	s_add_i32 s66, s66, s31
	s_cmpk_lg_i32 s34, 0x100
	s_cbranch_scc1 .Lgt_plain
	s_cmpk_lt_i32 s69, 0x200
	s_cbranch_scc1 .Lgt_go
	s_cmpk_gt_i32 s69, 0x27f
	s_cbranch_scc1 .LBB0_802
	s_sub_i32 s100, s69, 0x200
	s_and_b32 s98, s100, 3
	s_lshr_b32 s100, s100, 2
	s_add_i32 s69, s100, 0x200
	s_lshl_b32 s3, s69, 4
	s_add_i32 s3, s3, 0xffffe000
	s_add_i32 s40, s3, 16
	s_add_i32 s41, s3, 32
	s_add_i32 s62, s3, 48
	s_add_i32 s63, s3, 64
	s_add_i32 s64, s3, 0x50
	s_add_i32 s65, s3, 0x60
	s_add_i32 s66, s3, 0x70
	s_lshl_b32 s99, s98, 10
	s_add_i32 s99, s99, 0x400
	s_branch .Lgt_go
.Lgt_plain:
	s_cmpk_gt_i32 s69, 0x21f
	s_cbranch_scc1 .LBB0_802

.LBB0_1372:
	s_add_i32 s52, s52, 1
	s_mul_i32 s6, s52, s55
	s_mul_hi_u32 s7, s52, s56
	s_add_i32 s7, s7, s6
	s_mul_i32 s6, s52, s56
	s_add_u32 s24, s6, s2
	s_addc_u32 s25, s7, s47
	s_mov_b32 s99, s98
	s_cmp_ge_u32 s24, 0x400
	s_cselect_b32 s98, 8, 0
	s_cmpk_lg_i32 s34, 0x100
	s_cselect_b32 s98, 0, s98
	s_xor_b32 s24, s24, s98
	v_cmp_gt_i64_e32 vcc, s[24:25], v[166:167]
	v_cmp_lt_i64_e64 s[6:7], s[24:25], v[164:165]
	s_cbranch_vccnz .LBB0_1374
	s_ashr_i32 s20, s24, 31
	s_lshr_b32 s20, s20, 29
	s_add_i32 s20, s24, s20
	s_ashr_i32 s21, s20, 3
	s_and_b32 s20, s20, -8
	s_sub_i32 s20, s24, s20
	s_cmp_lt_i32 s20, 0
	s_cselect_b32 s22, s48, 0x81
	s_mul_i32 s20, s20, s22
	s_add_i32 s20, s20, s21
	s_ashr_i32 s21, s20, 31
	s_lshr_b32 s21, s21, 27
	s_add_i32 s21, s20, s21
	s_ashr_i32 s22, s21, 5
	s_lshl_b32 s22, s22, 3
	s_sub_i32 s23, 0x102, s22
	s_min_i32 s23, s23, 8
	s_abs_i32 s24, s23
	v_cvt_f32_u32_e32 v0, s24
	s_sub_i32 s26, 0, s24
	s_andn2_b32 s21, s21, 31
	s_sub_i32 s21, s20, s21
	v_rcp_iflag_f32_e32 v0, v0
	s_abs_i32 s20, s21
	s_xor_b32 s25, s21, s23
	s_ashr_i32 s25, s25, 31
	v_mul_f32_e32 v0, 0x4f7ffffe, v0
	v_cvt_u32_f32_e32 v0, v0
	s_nop 0
	v_readfirstlane_b32 s27, v0
	s_mul_i32 s26, s26, s27
	s_mul_hi_u32 s26, s27, s26
	s_add_i32 s27, s27, s26
	s_mul_hi_u32 s26, s20, s27
	s_mul_i32 s27, s26, s24
	s_sub_i32 s20, s20, s27
	s_add_i32 s44, s26, 1
	s_sub_i32 s27, s20, s24
	s_cmp_ge_u32 s20, s24
	s_cselect_b32 s26, s44, s26
	s_cselect_b32 s20, s27, s20
	s_add_i32 s27, s26, 1
	s_cmp_ge_u32 s20, s24
	s_cselect_b32 s20, s27, s26
	s_xor_b32 s20, s20, s25
	s_sub_i32 s20, s20, s25
	s_mul_i32 s23, s20, s23
	s_sub_i32 s21, s21, s23
	s_add_i32 s22, s22, s21
